# v31 + split-phase grid barrier #1 for the stream-first workgroups: they arrive but do not wait (their cache_k stream needs nothing from P0); the wait for the release word + buffer_inv happens after th
# speedup vs baseline: 1.0182x; 1.0149x over previous
.LBB0_113:
	s_or_b64 exec, exec, s[8:9]
	v_cvt_f32_u32_e32 v6, v4
	s_waitcnt vmcnt(0)
	v_readfirstlane_b32 s0, v5
	v_sub_u32_e32 v5, 0, v4
	v_rcp_iflag_f32_e32 v6, v6
	v_add_u32_e32 v7, s0, v3
	v_mul_f32_e32 v6, 0x4f7ffffe, v6
	v_cvt_u32_f32_e32 v6, v6
	v_mul_lo_u32 v3, v5, v6
	v_mul_hi_u32 v3, v6, v3
	v_add_u32_e32 v3, v6, v3
	v_mul_hi_u32 v3, v7, v3
	v_mul_lo_u32 v5, v3, v4
	v_sub_u32_e32 v5, v7, v5
	v_add_u32_e32 v6, 1, v3
	v_cmp_ge_u32_e32 vcc, v5, v4
	s_nop 1
	v_cndmask_b32_e32 v3, v3, v6, vcc
	v_sub_u32_e32 v6, v5, v4
	v_cndmask_b32_e32 v5, v5, v6, vcc
	v_add_u32_e32 v6, 1, v3
	v_cmp_ge_u32_e32 vcc, v5, v4
	v_add_u32_e32 v5, 1, v7
	s_nop 0
	v_cndmask_b32_e32 v3, v3, v6, vcc
	v_mul_lo_u32 v6, v4, v3
	v_add_u32_e32 v4, v6, v4
	v_cmp_ne_u32_e32 vcc, v5, v4
	s_and_saveexec_b64 s[0:1], vcc
	s_xor_b64 s[6:7], exec, s[0:1]
	s_cbranch_execz .LBB0_127
	s_bitcmp1_b32 s70, 3
	s_cbranch_scc1 .LBB0_127
	s_waitcnt lgkmcnt(0)
	v_readlane_b32 s10, v251, 38
	v_readlane_b32 s11, v251, 39
	v_mov_b32_e32 v2, 0
	s_nop 3
	s_add_u32 s10, s10, 0x3500
	s_addc_u32 s11, s11, 0
	global_load_dword v2, v2, s[10:11] sc1
	s_waitcnt vmcnt(0)
	v_cmp_eq_u32_e32 vcc, v2, v3
	s_and_saveexec_b64 s[8:9], vcc
	s_cbranch_execz .LBB0_126
	s_mov_b32 s0, 1
	s_mov_b64 s[12:13], 0
	v_mov_b32_e32 v2, 0
	s_branch .LBB0_117

.LBB0_165:
	s_barrier
	s_mov_b64 s[100:101], exec
	v_readlane_b32 s98, v251, 41
	v_readlane_b32 s99, v251, 42
	s_and_b64 s[98:99], s[100:101], s[98:99]
	s_mov_b64 exec, s[98:99]
	s_cbranch_execz .Lmy_dw_done
	v_readlane_b32 s98, v251, 38
	v_readlane_b32 s99, v251, 39
	s_add_u32 s98, s98, 0x3500
	s_addc_u32 s99, s99, 0
	v_mov_b32_e32 v252, s98
	v_mov_b32_e32 v253, s99
	s_mov_b32 s99, 0
.Lmy_dw_loop:
	global_load_dword v254, v[252:253], off sc1
	s_waitcnt vmcnt(0)
	v_readfirstlane_b32 s98, v254
	s_cmp_lg_u32 s98, 0
	s_cbranch_scc1 .Lmy_dw_ok
	s_sleep 1
	s_add_u32 s99, s99, 1
	s_cmp_lt_u32 s99, 0x4000
	s_cbranch_scc1 .Lmy_dw_loop
.Lmy_dw_ok:
	buffer_inv sc1
	s_waitcnt vmcnt(0)
.Lmy_dw_done:
	s_mov_b64 exec, s[100:101]
	s_barrier
